# final RMSNorm phase: rows double-buffered (next row loads in flight), gain vector loaded once
# speedup vs baseline: 1.0790x; 1.0001x over previous
; #define KP(f) ((decltype(Params::f))karg_ptr<(int)offsetof(Params, f)>())
; __device__ void phase_final() {
;     float* out = KP(out); const float* ssq = KP(ssq); const float* fg = KP(final_g);
;     const int lane = threadIdx.x & 63, gw = blockIdx.x * 8 + (threadIdx.x >> 6), nw = gridDim.x * 8;
;     for (int row = gw; row < T_ALL; row += nw) {
;         const float rs = row_rstd(ssq, row);
;         float* xr = out + (size_t)row * DM;
; #pragma unroll
;         for (int i = 0; i < 4; ++i) { const int c = i * 256 + lane * 4; const f32x4 v = *(const f32x4*)(xr + c); const f32x4 g = *(const f32x4*)(fg + c);
;             *(f32x4*)(xr + c) = v * rs * g; }
;     }
; }
.LBB0_2319:
	s_or_b64 exec, exec, s[6:7]
	s_waitcnt lgkmcnt(0)
	s_barrier
	v_readlane_b32 s8, v230, 4
	s_load_dwordx2 s[2:3], s[0:1], 0xd8
	s_waitcnt lgkmcnt(0)
	s_load_dwordx2 s[4:5], s[0:1], 0x128
	s_waitcnt lgkmcnt(0)
	s_load_dwordx2 s[0:1], s[0:1], 0xd0
	s_waitcnt lgkmcnt(0)
	v_readlane_b32 s9, v230, 5
	s_and_saveexec_b64 s[6:7], s[8:9]
	s_cbranch_execz .LBB0_2322
	v_lshlrev_b32_e32 v0, 4, v166
	v_lshlrev_b64 v[2:3], 6, v[144:145]
	v_lshlrev_b64 v[4:5], 12, v[144:145]
	v_and_b32_e32 v0, 0x3f0, v0
	v_mov_b32_e32 v1, 0
	v_lshl_add_u64 v[2:3], s[4:5], 0, v[2:3]
	s_ashr_i32 s51, s50, 31
	v_lshl_or_b32 v4, v167, 4, v4
	v_lshl_add_u64 v[0:1], s[0:1], 0, v[0:1]
	v_lshl_add_u64 v[2:3], v[2:3], 0, 32
	s_lshl_b64 s[0:1], s[50:51], 6
	v_lshl_add_u64 v[4:5], s[2:3], 0, v[4:5]
	s_lshl_b64 s[2:3], s[50:51], 12
	s_mov_b64 s[4:5], 0
	v_mov_b32_e32 v6, 0x358637bd
	s_mov_b32 s6, 0x800000
	s_movk_i32 s7, 0x43ff
	global_load_dwordx4 v[40:43], v[0:1], off
	global_load_dwordx4 v[44:47], v[0:1], off offset:1024
	global_load_dwordx4 v[48:51], v[0:1], off offset:2048
	global_load_dwordx4 v[52:55], v[0:1], off offset:3072
	v_mov_b64_e32 v[92:93], v[4:5]
	global_load_dwordx4 v[8:11], v[2:3], off offset:-32
	global_load_dwordx4 v[12:15], v[2:3], off offset:-16
	global_load_dwordx4 v[16:19], v[2:3], off
	global_load_dwordx4 v[20:23], v[2:3], off offset:16
	global_load_dwordx4 v[24:27], v[4:5], off
	global_load_dwordx4 v[28:31], v[4:5], off offset:1024
	global_load_dwordx4 v[32:35], v[4:5], off offset:2048
	global_load_dwordx4 v[36:39], v[4:5], off offset:3072
	v_add_u32_e32 v144, s50, v144
	v_lshl_add_u64 v[2:3], v[2:3], 0, s[0:1]
	v_lshl_add_u64 v[4:5], v[4:5], 0, s[2:3]
	v_cmp_ge_i32_e32 vcc, s7, v144
	s_cbranch_vccz .Lfin_lastA
	v_mov_b64_e32 v[94:95], v[4:5]
	global_load_dwordx4 v[56:59], v[2:3], off offset:-32
	global_load_dwordx4 v[60:63], v[2:3], off offset:-16
	global_load_dwordx4 v[64:67], v[2:3], off
	global_load_dwordx4 v[68:71], v[2:3], off offset:16
	global_load_dwordx4 v[72:75], v[4:5], off
	global_load_dwordx4 v[76:79], v[4:5], off offset:1024
	global_load_dwordx4 v[80:83], v[4:5], off offset:2048
	global_load_dwordx4 v[84:87], v[4:5], off offset:3072
	s_waitcnt vmcnt(8)
	v_add_f32_e32 v96, v8, v9
	v_add_f32_e32 v97, v10, v11
	v_add_f32_e32 v98, v12, v13
	v_add_f32_e32 v99, v14, v15
	v_add_f32_e32 v100, v16, v17
	v_add_f32_e32 v101, v18, v19
	v_add_f32_e32 v102, v20, v21
	v_add_f32_e32 v103, v22, v23
	v_add_f32_e32 v96, v96, v97
	v_add_f32_e32 v98, v98, v99
	v_add_f32_e32 v100, v100, v101
	v_add_f32_e32 v102, v102, v103
	v_add_f32_e32 v96, v96, v98
	v_add_f32_e32 v96, v96, v100
	v_add_f32_e32 v96, v96, v102
	v_fmamk_f32 v96, v96, 0x3a800000, v6
	v_mul_f32_e32 v97, 0x4b800000, v96
	v_cmp_gt_f32_e32 vcc, s6, v96
	s_nop 1
	v_cndmask_b32_e32 v96, v96, v97, vcc
	v_rsq_f32_e32 v96, v96
	s_nop 0
	v_mul_f32_e32 v97, 0x45800000, v96
	v_cndmask_b32_e32 v90, v96, v97, vcc
	v_pk_mul_f32 v[24:25], v[24:25], v[90:91] op_sel_hi:[1,0]
	v_pk_mul_f32 v[26:27], v[26:27], v[90:91] op_sel_hi:[1,0]
	v_pk_mul_f32 v[24:25], v[40:41], v[24:25]
	v_pk_mul_f32 v[26:27], v[42:43], v[26:27]
	global_store_dwordx4 v[92:93], v[24:27], off
	v_pk_mul_f32 v[28:29], v[28:29], v[90:91] op_sel_hi:[1,0]
	v_pk_mul_f32 v[30:31], v[30:31], v[90:91] op_sel_hi:[1,0]
	v_pk_mul_f32 v[28:29], v[44:45], v[28:29]
	v_pk_mul_f32 v[30:31], v[46:47], v[30:31]
	global_store_dwordx4 v[92:93], v[28:31], off offset:1024
	v_pk_mul_f32 v[32:33], v[32:33], v[90:91] op_sel_hi:[1,0]
	v_pk_mul_f32 v[34:35], v[34:35], v[90:91] op_sel_hi:[1,0]
	v_pk_mul_f32 v[32:33], v[48:49], v[32:33]
	v_pk_mul_f32 v[34:35], v[50:51], v[34:35]
	global_store_dwordx4 v[92:93], v[32:35], off offset:2048
	v_pk_mul_f32 v[36:37], v[36:37], v[90:91] op_sel_hi:[1,0]
	v_pk_mul_f32 v[38:39], v[38:39], v[90:91] op_sel_hi:[1,0]
	v_pk_mul_f32 v[36:37], v[52:53], v[36:37]
	v_pk_mul_f32 v[38:39], v[54:55], v[38:39]
	global_store_dwordx4 v[92:93], v[36:39], off offset:3072
.Lfin_loop:
	v_add_u32_e32 v144, s50, v144
	v_lshl_add_u64 v[2:3], v[2:3], 0, s[0:1]
	v_lshl_add_u64 v[4:5], v[4:5], 0, s[2:3]
	v_cmp_ge_i32_e32 vcc, s7, v144
	s_cbranch_vccz .Lfin_lastB
	v_mov_b64_e32 v[92:93], v[4:5]
	global_load_dwordx4 v[8:11], v[2:3], off offset:-32
	global_load_dwordx4 v[12:15], v[2:3], off offset:-16
	global_load_dwordx4 v[16:19], v[2:3], off
	global_load_dwordx4 v[20:23], v[2:3], off offset:16
	global_load_dwordx4 v[24:27], v[4:5], off
	global_load_dwordx4 v[28:31], v[4:5], off offset:1024
	global_load_dwordx4 v[32:35], v[4:5], off offset:2048
	global_load_dwordx4 v[36:39], v[4:5], off offset:3072
	s_waitcnt vmcnt(12)
	v_add_f32_e32 v96, v56, v57
	v_add_f32_e32 v97, v58, v59
	v_add_f32_e32 v98, v60, v61
	v_add_f32_e32 v99, v62, v63
	v_add_f32_e32 v100, v64, v65
	v_add_f32_e32 v101, v66, v67
	v_add_f32_e32 v102, v68, v69
	v_add_f32_e32 v103, v70, v71
	v_add_f32_e32 v96, v96, v97
	v_add_f32_e32 v98, v98, v99
	v_add_f32_e32 v100, v100, v101
	v_add_f32_e32 v102, v102, v103
	v_add_f32_e32 v96, v96, v98
	v_add_f32_e32 v96, v96, v100
	v_add_f32_e32 v96, v96, v102
	v_fmamk_f32 v96, v96, 0x3a800000, v6
	v_mul_f32_e32 v97, 0x4b800000, v96
	v_cmp_gt_f32_e32 vcc, s6, v96
	s_nop 1
	v_cndmask_b32_e32 v96, v96, v97, vcc
	v_rsq_f32_e32 v96, v96
	s_nop 0
	v_mul_f32_e32 v97, 0x45800000, v96
	v_cndmask_b32_e32 v90, v96, v97, vcc
	v_pk_mul_f32 v[72:73], v[72:73], v[90:91] op_sel_hi:[1,0]
	v_pk_mul_f32 v[74:75], v[74:75], v[90:91] op_sel_hi:[1,0]
	v_pk_mul_f32 v[72:73], v[40:41], v[72:73]
	v_pk_mul_f32 v[74:75], v[42:43], v[74:75]
	global_store_dwordx4 v[94:95], v[72:75], off
	v_pk_mul_f32 v[76:77], v[76:77], v[90:91] op_sel_hi:[1,0]
	v_pk_mul_f32 v[78:79], v[78:79], v[90:91] op_sel_hi:[1,0]
	v_pk_mul_f32 v[76:77], v[44:45], v[76:77]
	v_pk_mul_f32 v[78:79], v[46:47], v[78:79]
	global_store_dwordx4 v[94:95], v[76:79], off offset:1024
	v_pk_mul_f32 v[80:81], v[80:81], v[90:91] op_sel_hi:[1,0]
	v_pk_mul_f32 v[82:83], v[82:83], v[90:91] op_sel_hi:[1,0]
	v_pk_mul_f32 v[80:81], v[48:49], v[80:81]
	v_pk_mul_f32 v[82:83], v[50:51], v[82:83]
	global_store_dwordx4 v[94:95], v[80:83], off offset:2048
	v_pk_mul_f32 v[84:85], v[84:85], v[90:91] op_sel_hi:[1,0]
	v_pk_mul_f32 v[86:87], v[86:87], v[90:91] op_sel_hi:[1,0]
	v_pk_mul_f32 v[84:85], v[52:53], v[84:85]
	v_pk_mul_f32 v[86:87], v[54:55], v[86:87]
	global_store_dwordx4 v[94:95], v[84:87], off offset:3072
	v_add_u32_e32 v144, s50, v144
	v_lshl_add_u64 v[2:3], v[2:3], 0, s[0:1]
	v_lshl_add_u64 v[4:5], v[4:5], 0, s[2:3]
	v_cmp_ge_i32_e32 vcc, s7, v144
	s_cbranch_vccz .Lfin_lastA
; __device__ void phase_final() {
;     ...
;     for (int row = gw; row < T_ALL; row += nw) {
;         const float rs = row_rstd(ssq, row);
;         float* xr = out + (size_t)row * DM;
; #pragma unroll
;         for (int i = 0; i < 4; ++i) { const int c = i * 256 + lane * 4; const f32x4 v = *(const f32x4*)(xr + c); const f32x4 g = *(const f32x4*)(fg + c);
;             *(f32x4*)(xr + c) = v * rs * g; }
;     }
	v_mov_b64_e32 v[94:95], v[4:5]
	global_load_dwordx4 v[56:59], v[2:3], off offset:-32
	global_load_dwordx4 v[60:63], v[2:3], off offset:-16
	global_load_dwordx4 v[64:67], v[2:3], off
	global_load_dwordx4 v[68:71], v[2:3], off offset:16
	global_load_dwordx4 v[72:75], v[4:5], off
	global_load_dwordx4 v[76:79], v[4:5], off offset:1024
	global_load_dwordx4 v[80:83], v[4:5], off offset:2048
	global_load_dwordx4 v[84:87], v[4:5], off offset:3072
	s_waitcnt vmcnt(12)
	v_add_f32_e32 v96, v8, v9
	v_add_f32_e32 v97, v10, v11
	v_add_f32_e32 v98, v12, v13
	v_add_f32_e32 v99, v14, v15
	v_add_f32_e32 v100, v16, v17
	v_add_f32_e32 v101, v18, v19
	v_add_f32_e32 v102, v20, v21
	v_add_f32_e32 v103, v22, v23
	v_add_f32_e32 v96, v96, v97
	v_add_f32_e32 v98, v98, v99
	v_add_f32_e32 v100, v100, v101
	v_add_f32_e32 v102, v102, v103
	v_add_f32_e32 v96, v96, v98
	v_add_f32_e32 v96, v96, v100
	v_add_f32_e32 v96, v96, v102
	v_fmamk_f32 v96, v96, 0x3a800000, v6
	v_mul_f32_e32 v97, 0x4b800000, v96
	v_cmp_gt_f32_e32 vcc, s6, v96
	s_nop 1
	v_cndmask_b32_e32 v96, v96, v97, vcc
	v_rsq_f32_e32 v96, v96
	s_nop 0
	v_mul_f32_e32 v97, 0x45800000, v96
	v_cndmask_b32_e32 v90, v96, v97, vcc
	v_pk_mul_f32 v[24:25], v[24:25], v[90:91] op_sel_hi:[1,0]
	v_pk_mul_f32 v[26:27], v[26:27], v[90:91] op_sel_hi:[1,0]
	v_pk_mul_f32 v[24:25], v[40:41], v[24:25]
	v_pk_mul_f32 v[26:27], v[42:43], v[26:27]
	global_store_dwordx4 v[92:93], v[24:27], off
	v_pk_mul_f32 v[28:29], v[28:29], v[90:91] op_sel_hi:[1,0]
	v_pk_mul_f32 v[30:31], v[30:31], v[90:91] op_sel_hi:[1,0]
	v_pk_mul_f32 v[28:29], v[44:45], v[28:29]
	v_pk_mul_f32 v[30:31], v[46:47], v[30:31]
	global_store_dwordx4 v[92:93], v[28:31], off offset:1024
	v_pk_mul_f32 v[32:33], v[32:33], v[90:91] op_sel_hi:[1,0]
	v_pk_mul_f32 v[34:35], v[34:35], v[90:91] op_sel_hi:[1,0]
	v_pk_mul_f32 v[32:33], v[48:49], v[32:33]
	v_pk_mul_f32 v[34:35], v[50:51], v[34:35]
	global_store_dwordx4 v[92:93], v[32:35], off offset:2048
	v_pk_mul_f32 v[36:37], v[36:37], v[90:91] op_sel_hi:[1,0]
	v_pk_mul_f32 v[38:39], v[38:39], v[90:91] op_sel_hi:[1,0]
	v_pk_mul_f32 v[36:37], v[52:53], v[36:37]
	v_pk_mul_f32 v[38:39], v[54:55], v[38:39]
	global_store_dwordx4 v[92:93], v[36:39], off offset:3072
	s_branch .Lfin_loop
.Lfin_lastA:
	s_waitcnt vmcnt(0)
	v_add_f32_e32 v96, v8, v9
	v_add_f32_e32 v97, v10, v11
	v_add_f32_e32 v98, v12, v13
	v_add_f32_e32 v99, v14, v15
	v_add_f32_e32 v100, v16, v17
	v_add_f32_e32 v101, v18, v19
	v_add_f32_e32 v102, v20, v21
	v_add_f32_e32 v103, v22, v23
	v_add_f32_e32 v96, v96, v97
	v_add_f32_e32 v98, v98, v99
	v_add_f32_e32 v100, v100, v101
	v_add_f32_e32 v102, v102, v103
	v_add_f32_e32 v96, v96, v98
	v_add_f32_e32 v96, v96, v100
	v_add_f32_e32 v96, v96, v102
	v_fmamk_f32 v96, v96, 0x3a800000, v6
	v_mul_f32_e32 v97, 0x4b800000, v96
	v_cmp_gt_f32_e32 vcc, s6, v96
	s_nop 1
	v_cndmask_b32_e32 v96, v96, v97, vcc
	v_rsq_f32_e32 v96, v96
	s_nop 0
	v_mul_f32_e32 v97, 0x45800000, v96
	v_cndmask_b32_e32 v90, v96, v97, vcc
	v_pk_mul_f32 v[24:25], v[24:25], v[90:91] op_sel_hi:[1,0]
	v_pk_mul_f32 v[26:27], v[26:27], v[90:91] op_sel_hi:[1,0]
	v_pk_mul_f32 v[24:25], v[40:41], v[24:25]
	v_pk_mul_f32 v[26:27], v[42:43], v[26:27]
	global_store_dwordx4 v[92:93], v[24:27], off
	v_pk_mul_f32 v[28:29], v[28:29], v[90:91] op_sel_hi:[1,0]
	v_pk_mul_f32 v[30:31], v[30:31], v[90:91] op_sel_hi:[1,0]
	v_pk_mul_f32 v[28:29], v[44:45], v[28:29]
	v_pk_mul_f32 v[30:31], v[46:47], v[30:31]
	global_store_dwordx4 v[92:93], v[28:31], off offset:1024
	v_pk_mul_f32 v[32:33], v[32:33], v[90:91] op_sel_hi:[1,0]
	v_pk_mul_f32 v[34:35], v[34:35], v[90:91] op_sel_hi:[1,0]
	v_pk_mul_f32 v[32:33], v[48:49], v[32:33]
	v_pk_mul_f32 v[34:35], v[50:51], v[34:35]
	global_store_dwordx4 v[92:93], v[32:35], off offset:2048
	v_pk_mul_f32 v[36:37], v[36:37], v[90:91] op_sel_hi:[1,0]
	v_pk_mul_f32 v[38:39], v[38:39], v[90:91] op_sel_hi:[1,0]
	v_pk_mul_f32 v[36:37], v[52:53], v[36:37]
	v_pk_mul_f32 v[38:39], v[54:55], v[38:39]
	global_store_dwordx4 v[92:93], v[36:39], off offset:3072
	s_branch .LBB0_2322
.Lfin_lastB:
	s_waitcnt vmcnt(0)
	v_add_f32_e32 v96, v56, v57
	v_add_f32_e32 v97, v58, v59
	v_add_f32_e32 v98, v60, v61
	v_add_f32_e32 v99, v62, v63
	v_add_f32_e32 v100, v64, v65
	v_add_f32_e32 v101, v66, v67
	v_add_f32_e32 v102, v68, v69
	v_add_f32_e32 v103, v70, v71
	v_add_f32_e32 v96, v96, v97
	v_add_f32_e32 v98, v98, v99
	v_add_f32_e32 v100, v100, v101
	v_add_f32_e32 v102, v102, v103
	v_add_f32_e32 v96, v96, v98
	v_add_f32_e32 v96, v96, v100
	v_add_f32_e32 v96, v96, v102
	v_fmamk_f32 v96, v96, 0x3a800000, v6
	v_mul_f32_e32 v97, 0x4b800000, v96
	v_cmp_gt_f32_e32 vcc, s6, v96
	s_nop 1
	v_cndmask_b32_e32 v96, v96, v97, vcc
	v_rsq_f32_e32 v96, v96
	s_nop 0
	v_mul_f32_e32 v97, 0x45800000, v96
	v_cndmask_b32_e32 v90, v96, v97, vcc
	v_pk_mul_f32 v[72:73], v[72:73], v[90:91] op_sel_hi:[1,0]
	v_pk_mul_f32 v[74:75], v[74:75], v[90:91] op_sel_hi:[1,0]
	v_pk_mul_f32 v[72:73], v[40:41], v[72:73]
	v_pk_mul_f32 v[74:75], v[42:43], v[74:75]
	global_store_dwordx4 v[94:95], v[72:75], off
	v_pk_mul_f32 v[76:77], v[76:77], v[90:91] op_sel_hi:[1,0]
	v_pk_mul_f32 v[78:79], v[78:79], v[90:91] op_sel_hi:[1,0]
	v_pk_mul_f32 v[76:77], v[44:45], v[76:77]
	v_pk_mul_f32 v[78:79], v[46:47], v[78:79]
	global_store_dwordx4 v[94:95], v[76:79], off offset:1024
	v_pk_mul_f32 v[80:81], v[80:81], v[90:91] op_sel_hi:[1,0]
	v_pk_mul_f32 v[82:83], v[82:83], v[90:91] op_sel_hi:[1,0]
	v_pk_mul_f32 v[80:81], v[48:49], v[80:81]
	v_pk_mul_f32 v[82:83], v[50:51], v[82:83]
	global_store_dwordx4 v[94:95], v[80:83], off offset:2048
	v_pk_mul_f32 v[84:85], v[84:85], v[90:91] op_sel_hi:[1,0]
	v_pk_mul_f32 v[86:87], v[86:87], v[90:91] op_sel_hi:[1,0]
	v_pk_mul_f32 v[84:85], v[52:53], v[84:85]
	v_pk_mul_f32 v[86:87], v[54:55], v[86:87]
	global_store_dwordx4 v[94:95], v[84:87], off offset:3072
